# v16 with the GEMM K-loop heads and the attention tile loop head aligned to 64 bytes
# speedup vs baseline: 1.0033x; 1.0033x over previous
;     DI bool next(int i, pg8::Unit& o) const { if (i == 0 && have) { o = u; return true; } return false; }
; template <class Epi, class Sched, bool ALIGN_EPI = false, bool SP2 = false>
; __device__ __forceinline__ void gemm_phase(PG8_LAS unsigned char* lds, const Gemm g, const Sched& S, const Epi& E, const int tid) {
;     ...
;         const bool has_next = S.next(ui + 1, nxt);
;         const char* nA = has_next ? (const char*)g.A + (size_t)nxt.pm * tstep : cA; const char* nB = has_next ? (const char*)g.Bt + (size_t)nxt.pn * tstep : cB;
;         for (int t = 0; t < nt; t += 2) {
;             const bool last = (t == nt - 2);
;             const char* a1 = cA + (size_t)(t + 1) * kstep;
;             const char* a2 = last ? nA : cA + (size_t)(t + 2) * kstep; const char* b2 = last ? nB : cB + (size_t)(t + 2) * kstep;
;     ...
; #pragma unroll
;         for (int a = 0; a < 2; ++a)
; #pragma unroll
;             for (int b = 0; b < 2; ++b)
; #pragma unroll
;                 for (int m = 0; m < 4; ++m)
; #pragma unroll
;                     for (int n = 0; n < 2; ++n) acc[a][b][m][n] = (f32x4){0.f, 0.f, 0.f, 0.f};
.LBB0_125:
	s_ashr_i32 s21, s20, 31
	s_lshl_b64 s[22:23], s[20:21], 19
	s_add_u32 s22, s70, s22
	s_addc_u32 s23, s71, s23
	s_and_b64 s[24:25], s[8:9], exec
	s_cselect_b32 s1, s23, s3
	s_cselect_b32 s21, s22, s2
	s_ashr_i32 s19, s18, 31
	s_lshl_b64 s[24:25], s[18:19], 19
	s_add_u32 s24, s30, s24
	s_addc_u32 s25, s31, s25
	s_and_b64 s[28:29], s[8:9], exec
	s_cselect_b32 s19, s25, s27
	s_cselect_b32 s51, s24, s26
	s_add_u32 s2, s2, 0x40080
	s_addc_u32 s3, s3, 0
	s_add_u32 s52, s26, 0x100
	v_mov_b32_e32 v0, 0
	s_addc_u32 s53, s27, 0
	s_mov_b32 s54, -2
	v_mov_b32_e32 v1, v0
	v_mov_b32_e32 v2, v0
	v_mov_b32_e32 v3, v0
	v_mov_b32_e32 v4, v0
	v_mov_b32_e32 v5, v0
	v_mov_b32_e32 v6, v0
	v_mov_b32_e32 v7, v0
	v_mov_b32_e32 v16, v0
	v_mov_b32_e32 v17, v0
	v_mov_b32_e32 v18, v0
	v_mov_b32_e32 v19, v0
	v_mov_b32_e32 v20, v0
	v_mov_b32_e32 v21, v0
	v_mov_b32_e32 v22, v0
	v_mov_b32_e32 v23, v0
	v_mov_b32_e32 v32, v0
	v_mov_b32_e32 v33, v0
	v_mov_b32_e32 v34, v0
	v_mov_b32_e32 v35, v0
	v_mov_b32_e32 v36, v0
	v_mov_b32_e32 v37, v0
	v_mov_b32_e32 v38, v0
	v_mov_b32_e32 v39, v0
	v_mov_b32_e32 v48, v0
	v_mov_b32_e32 v49, v0
	v_mov_b32_e32 v50, v0
	v_mov_b32_e32 v51, v0
	v_mov_b32_e32 v52, v0
	v_mov_b32_e32 v53, v0
	v_mov_b32_e32 v54, v0
	v_mov_b32_e32 v55, v0
	v_mov_b32_e32 v8, v0
	v_mov_b32_e32 v9, v0
	v_mov_b32_e32 v10, v0
	v_mov_b32_e32 v11, v0
	v_mov_b32_e32 v12, v0
	v_mov_b32_e32 v13, v0
	v_mov_b32_e32 v14, v0
	v_mov_b32_e32 v15, v0
	v_mov_b32_e32 v24, v0
	v_mov_b32_e32 v25, v0
	v_mov_b32_e32 v26, v0
	v_mov_b32_e32 v27, v0
	v_mov_b32_e32 v28, v0
	v_mov_b32_e32 v29, v0
	v_mov_b32_e32 v30, v0
	v_mov_b32_e32 v31, v0
	v_mov_b32_e32 v40, v0
	v_mov_b32_e32 v41, v0
	v_mov_b32_e32 v42, v0
	v_mov_b32_e32 v43, v0
	v_mov_b32_e32 v44, v0
	v_mov_b32_e32 v45, v0
	v_mov_b32_e32 v46, v0
	v_mov_b32_e32 v47, v0
	v_mov_b32_e32 v56, v0
	v_mov_b32_e32 v57, v0
	v_mov_b32_e32 v58, v0
	v_mov_b32_e32 v59, v0
	v_mov_b32_e32 v60, v0
	v_mov_b32_e32 v61, v0
	v_mov_b32_e32 v62, v0
	v_mov_b32_e32 v63, v0
	v_mov_b32_e32 v64, v0
	v_mov_b32_e32 v65, v0
	v_mov_b32_e32 v66, v0
	v_mov_b32_e32 v67, v0
	v_mov_b32_e32 v68, v0
	v_mov_b32_e32 v69, v0
	v_mov_b32_e32 v70, v0
	v_mov_b32_e32 v71, v0
	v_mov_b32_e32 v80, v0
	v_mov_b32_e32 v81, v0
	v_mov_b32_e32 v82, v0
	v_mov_b32_e32 v83, v0
	v_mov_b32_e32 v84, v0
	v_mov_b32_e32 v85, v0
	v_mov_b32_e32 v86, v0
	v_mov_b32_e32 v87, v0
	v_mov_b32_e32 v96, v0
	v_mov_b32_e32 v97, v0
	v_mov_b32_e32 v98, v0
	v_mov_b32_e32 v99, v0
	v_mov_b32_e32 v100, v0
	v_mov_b32_e32 v101, v0
	v_mov_b32_e32 v102, v0
	v_mov_b32_e32 v103, v0
	v_mov_b32_e32 v112, v0
	v_mov_b32_e32 v113, v0
	v_mov_b32_e32 v114, v0
	v_mov_b32_e32 v115, v0
	v_mov_b32_e32 v116, v0
	v_mov_b32_e32 v117, v0
	v_mov_b32_e32 v118, v0
	v_mov_b32_e32 v119, v0
	v_mov_b32_e32 v72, v0
	v_mov_b32_e32 v73, v0
	v_mov_b32_e32 v74, v0
	v_mov_b32_e32 v75, v0
	v_mov_b32_e32 v76, v0
	v_mov_b32_e32 v77, v0
	v_mov_b32_e32 v78, v0
	v_mov_b32_e32 v79, v0
	v_mov_b32_e32 v88, v0
	v_mov_b32_e32 v89, v0
	v_mov_b32_e32 v90, v0
	v_mov_b32_e32 v91, v0
	v_mov_b32_e32 v92, v0
	v_mov_b32_e32 v93, v0
	v_mov_b32_e32 v94, v0
	v_mov_b32_e32 v95, v0
	v_mov_b32_e32 v104, v0
	v_mov_b32_e32 v105, v0
	v_mov_b32_e32 v106, v0
	v_mov_b32_e32 v107, v0
	v_mov_b32_e32 v108, v0
	v_mov_b32_e32 v109, v0
	v_mov_b32_e32 v110, v0
	v_mov_b32_e32 v111, v0
	v_mov_b32_e32 v120, v0
	v_mov_b32_e32 v121, v0
	v_mov_b32_e32 v122, v0
	v_mov_b32_e32 v123, v0
	v_mov_b32_e32 v124, v0
	v_mov_b32_e32 v125, v0
	v_mov_b32_e32 v126, v0
	v_mov_b32_e32 v127, v0
	s_mov_b64 s[60:61], 0x80
	.p2alignl 6, 3212836864

; DI void attn_unit(LAS unsigned char* lds, int tid, const bf16* __restrict__ P, const bf16* __restrict__ Vt, bf16* MG, int b, int h, int qrow0, int jt0, int jt1,
;                   float lam, float oscale, const float* subg) {
;     ...
;     const int lane = tid & 63, wave = tid >> 6, r32 = lane & 31, hi = lane >> 5;
;     const int qb = wave >> 1, m = wave & 1;
;     const int qrow = qrow0 + qb * 32 + r32;
;     bf16x8 qf[4];
; #pragma unroll
;     for (int ks = 0; ks < 4; ++ks) qf[ks] = *(const bf16x8*)(P + (size_t)qrow * NIN + h * 128 + m * 64 + ks * 16 + hi * 8);
;     f32x16 O[4];
; #pragma unroll
;     for (int es = 0; es < 4; ++es)
; #pragma unroll
;         for (int i = 0; i < 16; ++i) O[es][i] = 0.f;
;     float mrun = 0.f, lrun = 0.f;
;     u32x4 kreg[2], vreg[2];
;     const bf16* vbase = Vt + (size_t)(b * 4 + h) * 128 * NKEY;
;     ...
;     const bool halfB = wave >= 4;
;     ...
;     __syncthreads();
;     ATT_LOADG(jt0);
;     int buf = 0, pbuf = 2;
;     for (int j = jt0; j < jt1; ++j) {
.LBB0_299:
	s_or_b64 exec, exec, s[2:3]
	s_lshl_b32 s17, s15, 7
	s_lshl_b32 s36, s17, 1
	s_mov_b64 s[40:41], s[36:37]
	v_writelane_b32 v253, s40, 6
	s_movk_i32 s15, 0x2200
	v_mad_i64_i32 v[102:103], s[2:3], v99, s15, 0
	v_writelane_b32 v253, s41, 7
	v_writelane_b32 v253, s42, 8
	v_mad_i64_i32 v[100:101], s[2:3], v100, s15, 0
	v_writelane_b32 v253, s43, 9
	s_bfe_u32 s2, s14, 0x10002
	v_writelane_b32 v253, s44, 10
	s_lshl_b32 s3, s2, 8
	v_writelane_b32 v253, s45, 11
	s_add_i32 s15, s9, s3
	s_lshl_b32 s3, s2, 12
	s_lshl_b32 s2, s2, 2
	v_writelane_b32 v253, s46, 12
	s_add_i32 s16, s12, s3
	s_add_i32 s2, s8, s2
	s_and_b32 s3, s13, 3
	v_writelane_b32 v253, s47, 13
	s_add_i32 s3, s2, s3
	v_writelane_b32 v253, s48, 14
	v_writelane_b32 v253, s49, 15
	s_add_u32 s18, s74, s36
	v_and_b32_e32 v177, 63, v98
	v_add_u32_e32 v178, v97, v176
	v_writelane_b32 v253, s50, 16
	s_addc_u32 s19, s75, 0
	v_mov_b32_e32 v97, v147
	v_and_b32_e32 v98, 7, v98
	v_writelane_b32 v253, s51, 17
	v_lshl_add_u64 v[160:161], s[18:19], 0, v[96:97]
	v_mad_i64_i32 v[96:97], s[18:19], s3, v217, v[102:103]
	v_lshlrev_b32_e32 v146, 4, v98
	v_writelane_b32 v253, s52, 18
	v_lshl_add_u64 v[96:97], v[96:97], 0, v[146:147]
	v_writelane_b32 v253, s53, 19
	v_lshl_add_u64 v[162:163], s[6:7], 0, v[96:97]
	v_mad_i64_i32 v[96:97], s[18:19], s3, v217, v[100:101]
	v_writelane_b32 v253, s54, 20
	v_lshl_add_u64 v[96:97], v[96:97], 0, v[146:147]
	v_ashrrev_i32_e32 v157, 31, v156
	v_add_f32_e32 v158, 0, v158
	s_mov_b32 s2, 1
	v_writelane_b32 v253, s55, 21
	v_lshl_add_u64 v[164:165], s[6:7], 0, v[96:97]
	s_mov_b32 s17, 0
	s_mov_b32 s21, 0
	s_mov_b32 s18, 1
	v_and_b32_e32 v209, 64, v210
	v_add_u32_e32 v209, 64, v209
	v_xor_b32_e32 v250, 32, v210
	v_cmp_lt_i32_e64 s[24:25], v250, v209
	s_nop 1
	v_cndmask_b32_e64 v209, v210, v250, s[24:25]
	v_lshlrev_b32_e32 v209, 2, v209
	.p2alignl 6, 3212836864

; template <class Epi, class Sched, bool ALIGN_EPI = false, bool SP2 = false>
; __device__ __forceinline__ void gemm_phase(PG8_LAS unsigned char* lds, const Gemm g, const Sched& S, const Epi& E, const int tid) {
;     ...
; #pragma unroll
;         for (int a = 0; a < 2; ++a)
; #pragma unroll
;             for (int b = 0; b < 2; ++b)
; #pragma unroll
;                 for (int m = 0; m < 4; ++m)
; #pragma unroll
;                     for (int n = 0; n < 2; ++n) acc[a][b][m][n] = (f32x4){0.f, 0.f, 0.f, 0.f};
;         cur = nxt; cA = nA; cB = nB; ++ui;
.LBB0_880:
	s_add_u32 s30, s30, 0x80
	s_addc_u32 s31, s31, 0
	s_add_u32 s57, s34, 0x100
	v_mov_b32_e32 v0, 0
	s_addc_u32 s58, s35, 0
	s_mov_b32 s34, 0
	v_mov_b32_e32 v1, v0
	v_mov_b32_e32 v2, v0
	v_mov_b32_e32 v3, v0
	v_mov_b32_e32 v4, v0
	v_mov_b32_e32 v5, v0
	v_mov_b32_e32 v6, v0
	v_mov_b32_e32 v7, v0
	v_mov_b32_e32 v8, v0
	v_mov_b32_e32 v9, v0
	v_mov_b32_e32 v10, v0
	v_mov_b32_e32 v11, v0
	v_mov_b32_e32 v12, v0
	v_mov_b32_e32 v13, v0
	v_mov_b32_e32 v14, v0
	v_mov_b32_e32 v15, v0
	v_mov_b32_e32 v16, v0
	v_mov_b32_e32 v17, v0
	v_mov_b32_e32 v18, v0
	v_mov_b32_e32 v19, v0
	v_mov_b32_e32 v20, v0
	v_mov_b32_e32 v21, v0
	v_mov_b32_e32 v22, v0
	v_mov_b32_e32 v23, v0
	v_mov_b32_e32 v24, v0
	v_mov_b32_e32 v25, v0
	v_mov_b32_e32 v26, v0
	v_mov_b32_e32 v27, v0
	v_mov_b32_e32 v28, v0
	v_mov_b32_e32 v29, v0
	v_mov_b32_e32 v30, v0
	v_mov_b32_e32 v31, v0
	v_mov_b32_e32 v64, v0
	v_mov_b32_e32 v65, v0
	v_mov_b32_e32 v66, v0
	v_mov_b32_e32 v67, v0
	v_mov_b32_e32 v68, v0
	v_mov_b32_e32 v69, v0
	v_mov_b32_e32 v70, v0
	v_mov_b32_e32 v71, v0
	v_mov_b32_e32 v72, v0
	v_mov_b32_e32 v73, v0
	v_mov_b32_e32 v74, v0
	v_mov_b32_e32 v75, v0
	v_mov_b32_e32 v76, v0
	v_mov_b32_e32 v77, v0
	v_mov_b32_e32 v78, v0
	v_mov_b32_e32 v79, v0
	v_mov_b32_e32 v80, v0
	v_mov_b32_e32 v81, v0
	v_mov_b32_e32 v82, v0
	v_mov_b32_e32 v83, v0
	v_mov_b32_e32 v84, v0
	v_mov_b32_e32 v85, v0
	v_mov_b32_e32 v86, v0
	v_mov_b32_e32 v87, v0
	v_mov_b32_e32 v88, v0
	v_mov_b32_e32 v89, v0
	v_mov_b32_e32 v90, v0
	v_mov_b32_e32 v91, v0
	v_mov_b32_e32 v92, v0
	v_mov_b32_e32 v93, v0
	v_mov_b32_e32 v94, v0
	v_mov_b32_e32 v95, v0
	v_mov_b32_e32 v32, v0
	v_mov_b32_e32 v33, v0
	v_mov_b32_e32 v34, v0
	v_mov_b32_e32 v35, v0
	v_mov_b32_e32 v36, v0
	v_mov_b32_e32 v37, v0
	v_mov_b32_e32 v38, v0
	v_mov_b32_e32 v39, v0
	v_mov_b32_e32 v40, v0
	v_mov_b32_e32 v41, v0
	v_mov_b32_e32 v42, v0
	v_mov_b32_e32 v43, v0
	v_mov_b32_e32 v44, v0
	v_mov_b32_e32 v45, v0
	v_mov_b32_e32 v46, v0
	v_mov_b32_e32 v47, v0
	v_mov_b32_e32 v48, v0
	v_mov_b32_e32 v49, v0
	v_mov_b32_e32 v50, v0
	v_mov_b32_e32 v51, v0
	v_mov_b32_e32 v52, v0
	v_mov_b32_e32 v53, v0
	v_mov_b32_e32 v54, v0
	v_mov_b32_e32 v55, v0
	v_mov_b32_e32 v56, v0
	v_mov_b32_e32 v57, v0
	v_mov_b32_e32 v58, v0
	v_mov_b32_e32 v59, v0
	v_mov_b32_e32 v60, v0
	v_mov_b32_e32 v61, v0
	v_mov_b32_e32 v62, v0
	v_mov_b32_e32 v63, v0
	v_mov_b32_e32 v96, v0
	v_mov_b32_e32 v97, v0
	v_mov_b32_e32 v98, v0
	v_mov_b32_e32 v99, v0
	v_mov_b32_e32 v100, v0
	v_mov_b32_e32 v101, v0
	v_mov_b32_e32 v102, v0
	v_mov_b32_e32 v103, v0
	v_mov_b32_e32 v104, v0
	v_mov_b32_e32 v105, v0
	v_mov_b32_e32 v106, v0
	v_mov_b32_e32 v107, v0
	v_mov_b32_e32 v108, v0
	v_mov_b32_e32 v109, v0
	v_mov_b32_e32 v110, v0
	v_mov_b32_e32 v111, v0
	v_mov_b32_e32 v112, v0
	v_mov_b32_e32 v113, v0
	v_mov_b32_e32 v114, v0
	v_mov_b32_e32 v115, v0
	v_mov_b32_e32 v116, v0
	v_mov_b32_e32 v117, v0
	v_mov_b32_e32 v118, v0
	v_mov_b32_e32 v119, v0
	v_mov_b32_e32 v120, v0
	v_mov_b32_e32 v121, v0
	v_mov_b32_e32 v122, v0
	v_mov_b32_e32 v123, v0
	v_mov_b32_e32 v124, v0
	v_mov_b32_e32 v125, v0
	v_mov_b32_e32 v126, v0
	v_mov_b32_e32 v127, v0
	s_mov_b64 s[68:69], 0x80
	.p2alignl 6, 3212836864

; #define PG8_STAGE(bufoff, gbase, voff) do { _Pragma("unroll") for (int _i = 0; _i < 2; ++_i) \
;         __builtin_amdgcn_global_load_lds((const unsigned*)((const char*)(gbase) + (voff)[_i]), (PG8_LAS unsigned*)(lds + (bufoff) + ldsw + _i * 8192), 16, 0, 0); } while (0)
; #define PG8_WAIT_V(n) asm volatile("s_waitcnt vmcnt(" #n ")" ::: "memory")
; #define PG8_BAR __builtin_amdgcn_s_barrier()
; template <class Epi, class Sched, bool ALIGN_EPI = false, bool SP2 = false>
; __device__ __forceinline__ void gemm_phase(PG8_LAS unsigned char* lds, const Gemm g, const Sched& S, const Epi& E, const int tid) {
;     ...
;     f32x4 acc[2][2][4][2];
; #pragma unroll
;     for (int a = 0; a < 2; ++a)
; #pragma unroll
;         for (int b = 0; b < 2; ++b)
; #pragma unroll
;             for (int m = 0; m < 4; ++m)
; #pragma unroll
;                 for (int n = 0; n < 2; ++n) acc[a][b][m][n] = (f32x4){0.f, 0.f, 0.f, 0.f};
;     ...
;         PG8_WAIT_V(2); PG8_BAR;
;         PG8_STAGE(PG8_SB(1, 0), cB + kstep, voffB); PG8_STAGE(PG8_SA(1, 0), cA + kstep, voffA); PG8_STAGE(PG8_SB(1, 1), cB + hstep + kstep, voffB);
;         PG8_WAIT_V(6); PG8_BAR;
.LBB0_906:
	s_lshr_b32 s20, s20, 5
	v_mov_b32_e32 v133, v147
	v_lshl_add_u64 v[4:5], s[14:15], 0, v[146:147]
	v_lshl_add_u64 v[6:7], s[14:15], 0, v[132:133]
	s_lshl_b32 s14, s20, 6
	s_and_b32 s14, s14, 0x80
	s_sub_i32 s14, 0x300, s14
	s_lshr_b32 s14, s14, 6
	v_lshl_add_u64 v[0:1], s[0:1], 0, v[146:147]
	s_and_b64 s[12:13], s[12:13], exec
	s_mov_b64 s[36:37], 0x80
	v_lshl_add_u64 v[2:3], s[0:1], 0, v[132:133]
	v_mov_b32_e32 v129, v147
	s_cselect_b32 s26, s14, 4
	s_add_i32 m0, s21, 0x18000
	v_lshl_add_u64 v[0:1], v[0:1], 0, s[36:37]
	v_lshl_add_u64 v[8:9], s[2:3], 0, v[128:129]
	v_mov_b32_e32 v131, v147
	s_lshl_b32 s20, s27, 6
	s_lshl_b32 s12, s27, 13
	s_waitcnt vmcnt(2)
	s_barrier
	global_load_lds_dwordx4 v[0:1], off
	v_lshl_add_u64 v[0:1], v[2:3], 0, s[36:37]
	s_add_i32 m0, s21, 0x1a000
	s_add_i32 s27, s21, 0x8000
	v_lshl_add_u64 v[10:11], s[2:3], 0, v[130:131]
	global_load_lds_dwordx4 v[0:1], off
	v_lshl_add_u64 v[0:1], v[8:9], 0, s[36:37]
	s_mov_b32 m0, s27
	s_add_i32 s28, s21, 0xa000
	global_load_lds_dwordx4 v[0:1], off
	v_lshl_add_u64 v[0:1], v[10:11], 0, s[36:37]
	s_mov_b32 m0, s28
	v_lshlrev_b32_e32 v13, 2, v141
	global_load_lds_dwordx4 v[0:1], off
	s_add_i32 m0, s21, 0x1c000
	v_lshl_add_u64 v[0:1], v[4:5], 0, s[36:37]
	global_load_lds_dwordx4 v[0:1], off
	v_lshl_add_u64 v[0:1], v[6:7], 0, s[36:37]
	s_add_i32 m0, s21, 0x1e000
	v_lshl_or_b32 v12, v141, 6, v221
	global_load_lds_dwordx4 v[0:1], off
	v_and_b32_e32 v13, 32, v13
	v_bitop3_b32 v12, v12, s12, v13 bitop3:0xde
	s_lshl_b32 s12, s25, 5
	s_waitcnt vmcnt(6)
	s_and_b32 s25, s12, 0x60
	v_mov_b32_e32 v0, 0
	v_readlane_b32 s40, v253, 6
	v_lshl_or_b32 v134, s25, 7, v222
	s_add_i32 s29, s26, -2
	s_mov_b32 s14, 0
	v_add_u32_e32 v135, 0, v12
	v_mov_b32_e32 v1, v0
	v_mov_b32_e32 v2, v0
	v_mov_b32_e32 v3, v0
	v_mov_b32_e32 v4, v0
	v_mov_b32_e32 v5, v0
	v_mov_b32_e32 v6, v0
	v_mov_b32_e32 v7, v0
	v_mov_b32_e32 v12, v0
	v_mov_b32_e32 v13, v0
	v_mov_b32_e32 v14, v0
	v_mov_b32_e32 v15, v0
	v_mov_b32_e32 v16, v0
	v_mov_b32_e32 v17, v0
	v_mov_b32_e32 v18, v0
	v_mov_b32_e32 v19, v0
	v_mov_b32_e32 v28, v0
	v_mov_b32_e32 v29, v0
	v_mov_b32_e32 v30, v0
	v_mov_b32_e32 v31, v0
	v_mov_b32_e32 v32, v0
	v_mov_b32_e32 v33, v0
	v_mov_b32_e32 v34, v0
	v_mov_b32_e32 v35, v0
	v_mov_b32_e32 v44, v0
	v_mov_b32_e32 v45, v0
	v_mov_b32_e32 v46, v0
	v_mov_b32_e32 v47, v0
	v_mov_b32_e32 v48, v0
	v_mov_b32_e32 v49, v0
	v_mov_b32_e32 v50, v0
	v_mov_b32_e32 v51, v0
	v_mov_b32_e32 v8, v0
	v_mov_b32_e32 v9, v0
	v_mov_b32_e32 v10, v0
	v_mov_b32_e32 v11, v0
	v_mov_b32_e32 v20, v0
	v_mov_b32_e32 v21, v0
	v_mov_b32_e32 v22, v0
	v_mov_b32_e32 v23, v0
	v_mov_b32_e32 v24, v0
	v_mov_b32_e32 v25, v0
	v_mov_b32_e32 v26, v0
	v_mov_b32_e32 v27, v0
	v_mov_b32_e32 v36, v0
	v_mov_b32_e32 v37, v0
	v_mov_b32_e32 v38, v0
	v_mov_b32_e32 v39, v0
	v_mov_b32_e32 v40, v0
	v_mov_b32_e32 v41, v0
	v_mov_b32_e32 v42, v0
	v_mov_b32_e32 v43, v0
	v_mov_b32_e32 v52, v0
	v_mov_b32_e32 v53, v0
	v_mov_b32_e32 v54, v0
	v_mov_b32_e32 v55, v0
	v_mov_b32_e32 v56, v0
	v_mov_b32_e32 v57, v0
	v_mov_b32_e32 v58, v0
	v_mov_b32_e32 v59, v0
	v_mov_b32_e32 v60, v0
	v_mov_b32_e32 v61, v0
	v_mov_b32_e32 v62, v0
	v_mov_b32_e32 v63, v0
	v_mov_b32_e32 v64, v0
	v_mov_b32_e32 v65, v0
	v_mov_b32_e32 v66, v0
	v_mov_b32_e32 v67, v0
	v_mov_b32_e32 v68, v0
	v_mov_b32_e32 v69, v0
	v_mov_b32_e32 v70, v0
	v_mov_b32_e32 v71, v0
	v_mov_b32_e32 v76, v0
	v_mov_b32_e32 v77, v0
	v_mov_b32_e32 v78, v0
	v_mov_b32_e32 v79, v0
	v_mov_b32_e32 v84, v0
	v_mov_b32_e32 v85, v0
	v_mov_b32_e32 v86, v0
	v_mov_b32_e32 v87, v0
	v_mov_b32_e32 v92, v0
	v_mov_b32_e32 v93, v0
	v_mov_b32_e32 v94, v0
	v_mov_b32_e32 v95, v0
	v_mov_b32_e32 v100, v0
	v_mov_b32_e32 v101, v0
	v_mov_b32_e32 v102, v0
	v_mov_b32_e32 v103, v0
	v_mov_b32_e32 v108, v0
	v_mov_b32_e32 v109, v0
	v_mov_b32_e32 v110, v0
	v_mov_b32_e32 v111, v0
	v_mov_b32_e32 v116, v0
	v_mov_b32_e32 v117, v0
	v_mov_b32_e32 v118, v0
	v_mov_b32_e32 v119, v0
	v_mov_b32_e32 v72, v0
	v_mov_b32_e32 v73, v0
	v_mov_b32_e32 v74, v0
	v_mov_b32_e32 v75, v0
	v_mov_b32_e32 v80, v0
	v_mov_b32_e32 v81, v0
	v_mov_b32_e32 v82, v0
	v_mov_b32_e32 v83, v0
	v_mov_b32_e32 v88, v0
	v_mov_b32_e32 v89, v0
	v_mov_b32_e32 v90, v0
	v_mov_b32_e32 v91, v0
	v_mov_b32_e32 v96, v0
	v_mov_b32_e32 v97, v0
	v_mov_b32_e32 v98, v0
	v_mov_b32_e32 v99, v0
	v_mov_b32_e32 v104, v0
	v_mov_b32_e32 v105, v0
	v_mov_b32_e32 v106, v0
	v_mov_b32_e32 v107, v0
	v_mov_b32_e32 v112, v0
	v_mov_b32_e32 v113, v0
	v_mov_b32_e32 v114, v0
	v_mov_b32_e32 v115, v0
	v_mov_b32_e32 v124, v0
	v_mov_b32_e32 v125, v0
	v_mov_b32_e32 v126, v0
	v_mov_b32_e32 v127, v0
	v_mov_b32_e32 v120, v0
	v_mov_b32_e32 v121, v0
	v_mov_b32_e32 v122, v0
	v_mov_b32_e32 v123, v0
	v_readlane_b32 s41, v253, 7
	s_barrier
	v_readlane_b32 s42, v253, 8
	v_readlane_b32 s43, v253, 9
	v_readlane_b32 s44, v253, 10
	v_readlane_b32 s45, v253, 11
	v_readlane_b32 s46, v253, 12
	v_readlane_b32 s47, v253, 13
	v_readlane_b32 s48, v253, 14
	v_readlane_b32 s49, v253, 15
	v_readlane_b32 s50, v253, 16
	v_readlane_b32 s51, v253, 17
	v_readlane_b32 s52, v253, 18
	v_readlane_b32 s53, v253, 19
	v_readlane_b32 s54, v253, 20
	v_readlane_b32 s55, v253, 21
	.p2alignl 6, 3212836864

;     DI bool next(int i, pg8::Unit& o) const { if (i == 0 && have) { o = u; return true; } return false; }
; template <class Epi, class Sched, bool ALIGN_EPI = false, bool SP2 = false>
; __device__ __forceinline__ void gemm_phase(PG8_LAS unsigned char* lds, const Gemm g, const Sched& S, const Epi& E, const int tid) {
;     ...
;         const bool has_next = S.next(ui + 1, nxt);
;         const char* nA = has_next ? (const char*)g.A + (size_t)nxt.pm * tstep : cA; const char* nB = has_next ? (const char*)g.Bt + (size_t)nxt.pn * tstep : cB;
;         for (int t = 0; t < nt; t += 2) {
;             const bool last = (t == nt - 2);
;             const char* a1 = cA + (size_t)(t + 1) * kstep;
;             const char* a2 = last ? nA : cA + (size_t)(t + 2) * kstep; const char* b2 = last ? nB : cB + (size_t)(t + 2) * kstep;
;             const char* a3 = a2 + kstep; const char* b3 = b2 + kstep;
;     ...
; #pragma unroll
;         for (int a = 0; a < 2; ++a)
; #pragma unroll
;             for (int b = 0; b < 2; ++b)
; #pragma unroll
;                 for (int m = 0; m < 4; ++m)
; #pragma unroll
;                     for (int n = 0; n < 2; ++n) acc[a][b][m][n] = (f32x4){0.f, 0.f, 0.f, 0.f};
;         cur = nxt; cA = nA; cB = nB; ++ui;
.LBB0_920:
	s_ashr_i32 s9, s8, 31
	s_lshl_b64 s[10:11], s[8:9], 19
	s_add_u32 s10, s70, s10
	s_addc_u32 s11, s71, s11
	s_and_b64 s[12:13], s[0:1], exec
	s_cselect_b32 s9, s11, s17
	s_cselect_b32 s38, s10, s16
	s_ashr_i32 s7, s6, 31
	s_lshl_b64 s[12:13], s[6:7], 19
	s_add_u32 s12, s23, s12
	s_addc_u32 s13, s24, s13
	s_and_b64 s[20:21], s[0:1], exec
	s_cselect_b32 s7, s13, s19
	s_cselect_b32 s39, s12, s18
	s_add_u32 s16, s16, 0x40080
	s_addc_u32 s17, s17, 0
	s_add_u32 s40, s18, 0x100
	v_mov_b32_e32 v0, 0
	s_addc_u32 s41, s19, 0
	s_mov_b32 s42, -2
	v_mov_b32_e32 v1, v0
	v_mov_b32_e32 v2, v0
	v_mov_b32_e32 v3, v0
	v_mov_b32_e32 v8, v0
	v_mov_b32_e32 v9, v0
	v_mov_b32_e32 v10, v0
	v_mov_b32_e32 v11, v0
	v_mov_b32_e32 v16, v0
	v_mov_b32_e32 v17, v0
	v_mov_b32_e32 v18, v0
	v_mov_b32_e32 v19, v0
	v_mov_b32_e32 v20, v0
	v_mov_b32_e32 v21, v0
	v_mov_b32_e32 v22, v0
	v_mov_b32_e32 v23, v0
	v_mov_b32_e32 v32, v0
	v_mov_b32_e32 v33, v0
	v_mov_b32_e32 v34, v0
	v_mov_b32_e32 v35, v0
	v_mov_b32_e32 v36, v0
	v_mov_b32_e32 v37, v0
	v_mov_b32_e32 v38, v0
	v_mov_b32_e32 v39, v0
	v_mov_b32_e32 v48, v0
	v_mov_b32_e32 v49, v0
	v_mov_b32_e32 v50, v0
	v_mov_b32_e32 v51, v0
	v_mov_b32_e32 v52, v0
	v_mov_b32_e32 v53, v0
	v_mov_b32_e32 v54, v0
	v_mov_b32_e32 v55, v0
	v_mov_b32_e32 v4, v0
	v_mov_b32_e32 v5, v0
	v_mov_b32_e32 v6, v0
	v_mov_b32_e32 v7, v0
	v_mov_b32_e32 v12, v0
	v_mov_b32_e32 v13, v0
	v_mov_b32_e32 v14, v0
	v_mov_b32_e32 v15, v0
	v_mov_b32_e32 v24, v0
	v_mov_b32_e32 v25, v0
	v_mov_b32_e32 v26, v0
	v_mov_b32_e32 v27, v0
	v_mov_b32_e32 v28, v0
	v_mov_b32_e32 v29, v0
	v_mov_b32_e32 v30, v0
	v_mov_b32_e32 v31, v0
	v_mov_b32_e32 v40, v0
	v_mov_b32_e32 v41, v0
	v_mov_b32_e32 v42, v0
	v_mov_b32_e32 v43, v0
	v_mov_b32_e32 v44, v0
	v_mov_b32_e32 v45, v0
	v_mov_b32_e32 v46, v0
	v_mov_b32_e32 v47, v0
	v_mov_b32_e32 v56, v0
	v_mov_b32_e32 v57, v0
	v_mov_b32_e32 v58, v0
	v_mov_b32_e32 v59, v0
	v_mov_b32_e32 v60, v0
	v_mov_b32_e32 v61, v0
	v_mov_b32_e32 v62, v0
	v_mov_b32_e32 v63, v0
	v_mov_b32_e32 v64, v0
	v_mov_b32_e32 v65, v0
	v_mov_b32_e32 v66, v0
	v_mov_b32_e32 v67, v0
	v_mov_b32_e32 v68, v0
	v_mov_b32_e32 v69, v0
	v_mov_b32_e32 v70, v0
	v_mov_b32_e32 v71, v0
	v_mov_b32_e32 v80, v0
	v_mov_b32_e32 v81, v0
	v_mov_b32_e32 v82, v0
	v_mov_b32_e32 v83, v0
	v_mov_b32_e32 v84, v0
	v_mov_b32_e32 v85, v0
	v_mov_b32_e32 v86, v0
	v_mov_b32_e32 v87, v0
	v_mov_b32_e32 v96, v0
	v_mov_b32_e32 v97, v0
	v_mov_b32_e32 v98, v0
	v_mov_b32_e32 v99, v0
	v_mov_b32_e32 v100, v0
	v_mov_b32_e32 v101, v0
	v_mov_b32_e32 v102, v0
	v_mov_b32_e32 v103, v0
	v_mov_b32_e32 v112, v0
	v_mov_b32_e32 v113, v0
	v_mov_b32_e32 v114, v0
	v_mov_b32_e32 v115, v0
	v_mov_b32_e32 v116, v0
	v_mov_b32_e32 v117, v0
	v_mov_b32_e32 v118, v0
	v_mov_b32_e32 v119, v0
	v_mov_b32_e32 v72, v0
	v_mov_b32_e32 v73, v0
	v_mov_b32_e32 v74, v0
	v_mov_b32_e32 v75, v0
	v_mov_b32_e32 v76, v0
	v_mov_b32_e32 v77, v0
	v_mov_b32_e32 v78, v0
	v_mov_b32_e32 v79, v0
	v_mov_b32_e32 v88, v0
	v_mov_b32_e32 v89, v0
	v_mov_b32_e32 v90, v0
	v_mov_b32_e32 v91, v0
	v_mov_b32_e32 v92, v0
	v_mov_b32_e32 v93, v0
	v_mov_b32_e32 v94, v0
	v_mov_b32_e32 v95, v0
	v_mov_b32_e32 v104, v0
	v_mov_b32_e32 v105, v0
	v_mov_b32_e32 v106, v0
	v_mov_b32_e32 v107, v0
	v_mov_b32_e32 v108, v0
	v_mov_b32_e32 v109, v0
	v_mov_b32_e32 v110, v0
	v_mov_b32_e32 v111, v0
	v_mov_b32_e32 v120, v0
	v_mov_b32_e32 v121, v0
	v_mov_b32_e32 v122, v0
	v_mov_b32_e32 v123, v0
	v_mov_b32_e32 v124, v0
	v_mov_b32_e32 v125, v0
	v_mov_b32_e32 v126, v0
	v_mov_b32_e32 v127, v0
	s_mov_b64 s[48:49], 0x80
	.p2alignl 6, 3212836864
